# gate|up epilogue: row scale folded into the sigmoid denominator (one packed fma), the in-place row scalings of g and u removed; on top of the early sub-grid poll
# speedup vs baseline: 1.0036x; 1.0036x over previous
.LBB11_2572:
	s_or_b64 exec, exec, s[26:27]
	s_lshl_b32 s0, s42, 10
	v_mov_b32_e32 v148, v143
	v_mov_b32_e32 v149, v141
	s_add_i32 s0, s0, 0
	s_xor_b32 s42, s42, 1
	v_lshl_add_u32 v147, v149, 2, s0
	v_add_u32_e32 v147, 0x22000, v147
	ds_read_b32 v150, v147
	ds_read_b32 v170, v147 offset:64
	ds_read_b32 v172, v147 offset:128
	ds_read_b32 v174, v147 offset:192
	ds_read_b32 v176, v147 offset:512
	ds_read_b32 v178, v147 offset:576
	ds_read_b32 v180, v147 offset:640
	ds_read_b32 v190, v147 offset:704
	s_movk_i32 s0, 0xb00
	s_waitcnt lgkmcnt(0)
	v_mul_f32_e32 v152, 0xbfb8aa3b, v150
	v_mul_f32_e32 v192, v150, v150
	v_rcp_f32_e32 v192, v192
	s_nop 0
	v_pk_mul_f32 v[154:155], v[126:127], v[152:153] op_sel_hi:[1,0]
	v_pk_mul_f32 v[122:123], v[126:127], v[122:123]
	v_pk_mul_f32 v[126:127], v[128:129], v[152:153] op_sel_hi:[1,0]
	v_exp_f32_e32 v126, v126
	v_exp_f32_e32 v127, v127
	v_pk_mul_f32 v[124:125], v[128:129], v[124:125]
	v_exp_f32_e32 v154, v154
	v_pk_fma_f32 v[126:127], v[126:127], v[192:193], v[192:193] op_sel_hi:[1,0,0]
	v_exp_f32_e32 v155, v155
	v_rcp_f32_e32 v126, v126
	v_rcp_f32_e32 v127, v127
	v_pk_fma_f32 v[154:155], v[154:155], v[192:193], v[192:193] op_sel_hi:[1,0,0]
	v_pk_mul_f32 v[124:125], v[124:125], v[126:127]
	v_pk_mul_f32 v[126:127], v[118:119], v[152:153] op_sel_hi:[1,0]
	v_exp_f32_e32 v126, v126
	v_exp_f32_e32 v127, v127
	v_pk_mul_f32 v[114:115], v[118:119], v[114:115]
	v_pk_mul_f32 v[118:119], v[120:121], v[152:153] op_sel_hi:[1,0]
	v_rcp_f32_e32 v154, v154
	v_exp_f32_e32 v118, v118
	v_exp_f32_e32 v119, v119
	v_pk_fma_f32 v[126:127], v[126:127], v[192:193], v[192:193] op_sel_hi:[1,0,0]
	v_rcp_f32_e32 v155, v155
	v_rcp_f32_e32 v126, v126
	v_rcp_f32_e32 v127, v127
	v_pk_fma_f32 v[118:119], v[118:119], v[192:193], v[192:193] op_sel_hi:[1,0,0]
	v_rcp_f32_e32 v118, v118
	v_rcp_f32_e32 v119, v119
	v_pk_mul_f32 v[114:115], v[114:115], v[126:127]
	v_pk_mul_f32 v[116:117], v[120:121], v[116:117]
	v_lshl_add_u32 v126, s7, 8, v149
	v_pk_mul_f32 v[122:123], v[122:123], v[154:155]
	v_pk_mul_f32 v[120:121], v[116:117], v[118:119]
	v_cvt_pk_bf16_f32 v116, v122, v123
	v_cvt_pk_bf16_f32 v117, v124, v125
	v_cvt_pk_bf16_f32 v118, v114, v115
	v_mad_u64_u32 v[114:115], s[0:1], v126, s0, v[148:149]
	s_lshl_b32 s0, s6, 8
	s_nop 0
	v_lshl_add_u32 v114, v114, 1, s0
	v_cvt_pk_bf16_f32 v119, v120, v121
	buffer_store_dwordx4 v[116:119], v114, s[52:55], 0 offen sc1
	s_nop 1
	v_mul_f32_e32 v118, 0xbfb8aa3b, v170
	v_mul_f32_e32 v194, v170, v170
	v_rcp_f32_e32 v194, v194
	s_nop 0
	v_pk_mul_f32 v[120:121], v[110:111], v[118:119] op_sel_hi:[1,0]
	v_pk_mul_f32 v[106:107], v[110:111], v[106:107]
	v_pk_mul_f32 v[110:111], v[112:113], v[118:119] op_sel_hi:[1,0]
	v_exp_f32_e32 v110, v110
	v_exp_f32_e32 v111, v111
	v_pk_mul_f32 v[108:109], v[112:113], v[108:109]
	v_exp_f32_e32 v120, v120
	v_pk_fma_f32 v[110:111], v[110:111], v[194:195], v[194:195] op_sel_hi:[1,0,0]
	v_exp_f32_e32 v121, v121
	v_rcp_f32_e32 v110, v110
	v_rcp_f32_e32 v111, v111
	v_pk_fma_f32 v[120:121], v[120:121], v[194:195], v[194:195] op_sel_hi:[1,0,0]
	v_pk_mul_f32 v[108:109], v[108:109], v[110:111]
	v_pk_mul_f32 v[110:111], v[102:103], v[118:119] op_sel_hi:[1,0]
	v_exp_f32_e32 v110, v110
	v_exp_f32_e32 v111, v111
	v_pk_mul_f32 v[98:99], v[102:103], v[98:99]
	v_rcp_f32_e32 v120, v120
	v_rcp_f32_e32 v121, v121
	v_pk_fma_f32 v[110:111], v[110:111], v[194:195], v[194:195] op_sel_hi:[1,0,0]
	v_pk_mul_f32 v[106:107], v[106:107], v[120:121]
	v_rcp_f32_e32 v110, v110
	v_rcp_f32_e32 v111, v111
	s_nop 0
	v_pk_mul_f32 v[102:103], v[98:99], v[110:111]
	v_pk_mul_f32 v[98:99], v[104:105], v[118:119] op_sel_hi:[1,0]
	v_exp_f32_e32 v98, v98
	v_exp_f32_e32 v99, v99
	v_pk_mul_f32 v[100:101], v[104:105], v[100:101]
	v_pk_fma_f32 v[98:99], v[98:99], v[194:195], v[194:195] op_sel_hi:[1,0,0]
	s_nop 0
	v_rcp_f32_e32 v98, v98
	v_rcp_f32_e32 v99, v99
	s_nop 0
	v_pk_mul_f32 v[104:105], v[100:101], v[98:99]
	v_cvt_pk_bf16_f32 v98, v106, v107
	v_cvt_pk_bf16_f32 v99, v108, v109
	v_cvt_pk_bf16_f32 v100, v102, v103
	v_add_u32_e32 v102, 0x16000, v114
	v_cvt_pk_bf16_f32 v101, v104, v105
	buffer_store_dwordx4 v[98:101], v102, s[52:55], 0 offen sc1
	s_nop 1
	v_mul_f32_e32 v100, 0xbfb8aa3b, v172
	v_mul_f32_e32 v192, v172, v172
	v_rcp_f32_e32 v192, v192
	s_nop 0
	v_pk_mul_f32 v[102:103], v[94:95], v[100:101] op_sel_hi:[1,0]
	v_pk_mul_f32 v[90:91], v[94:95], v[90:91]
	v_pk_mul_f32 v[94:95], v[96:97], v[100:101] op_sel_hi:[1,0]
	v_exp_f32_e32 v94, v94
	v_exp_f32_e32 v95, v95
	v_pk_mul_f32 v[92:93], v[96:97], v[92:93]
	v_exp_f32_e32 v102, v102
	v_pk_fma_f32 v[94:95], v[94:95], v[192:193], v[192:193] op_sel_hi:[1,0,0]
	v_exp_f32_e32 v103, v103
	v_rcp_f32_e32 v94, v94
	v_rcp_f32_e32 v95, v95
	v_pk_fma_f32 v[102:103], v[102:103], v[192:193], v[192:193] op_sel_hi:[1,0,0]
	v_pk_mul_f32 v[92:93], v[92:93], v[94:95]
	v_pk_mul_f32 v[94:95], v[86:87], v[100:101] op_sel_hi:[1,0]
	v_exp_f32_e32 v94, v94
	v_exp_f32_e32 v95, v95
	v_pk_mul_f32 v[82:83], v[86:87], v[82:83]
	v_rcp_f32_e32 v102, v102
	v_rcp_f32_e32 v103, v103
	v_pk_fma_f32 v[94:95], v[94:95], v[192:193], v[192:193] op_sel_hi:[1,0,0]
	v_pk_mul_f32 v[90:91], v[90:91], v[102:103]
	v_rcp_f32_e32 v94, v94
	v_rcp_f32_e32 v95, v95
	s_nop 0
	v_pk_mul_f32 v[86:87], v[82:83], v[94:95]
	v_pk_mul_f32 v[82:83], v[88:89], v[100:101] op_sel_hi:[1,0]
	v_exp_f32_e32 v82, v82
	v_exp_f32_e32 v83, v83
	v_pk_mul_f32 v[84:85], v[88:89], v[84:85]
	v_pk_fma_f32 v[82:83], v[82:83], v[192:193], v[192:193] op_sel_hi:[1,0,0]
	s_nop 0
	v_rcp_f32_e32 v82, v82
	v_rcp_f32_e32 v83, v83
	s_nop 0
	v_pk_mul_f32 v[88:89], v[84:85], v[82:83]
	v_cvt_pk_bf16_f32 v82, v90, v91
	v_cvt_pk_bf16_f32 v83, v92, v93
	v_cvt_pk_bf16_f32 v84, v86, v87
	v_add_u32_e32 v86, 0x2c000, v114
	v_cvt_pk_bf16_f32 v85, v88, v89
	buffer_store_dwordx4 v[82:85], v86, s[52:55], 0 offen sc1
	s_nop 1
	v_mul_f32_e32 v84, 0xbfb8aa3b, v174
	v_mul_f32_e32 v194, v174, v174
	v_rcp_f32_e32 v194, v194
	s_nop 0
	v_pk_mul_f32 v[86:87], v[78:79], v[84:85] op_sel_hi:[1,0]
	v_pk_mul_f32 v[74:75], v[78:79], v[74:75]
	v_pk_mul_f32 v[78:79], v[80:81], v[84:85] op_sel_hi:[1,0]
	v_exp_f32_e32 v78, v78
	v_exp_f32_e32 v79, v79
	v_pk_mul_f32 v[76:77], v[80:81], v[76:77]
	v_exp_f32_e32 v86, v86
	v_pk_fma_f32 v[78:79], v[78:79], v[194:195], v[194:195] op_sel_hi:[1,0,0]
	v_exp_f32_e32 v87, v87
	v_rcp_f32_e32 v78, v78
	v_rcp_f32_e32 v79, v79
	v_pk_fma_f32 v[86:87], v[86:87], v[194:195], v[194:195] op_sel_hi:[1,0,0]
	v_pk_mul_f32 v[76:77], v[76:77], v[78:79]
	v_pk_mul_f32 v[78:79], v[70:71], v[84:85] op_sel_hi:[1,0]
	v_exp_f32_e32 v78, v78
	v_exp_f32_e32 v79, v79
	v_pk_mul_f32 v[66:67], v[70:71], v[66:67]
	v_rcp_f32_e32 v86, v86
	v_rcp_f32_e32 v87, v87
	v_pk_fma_f32 v[78:79], v[78:79], v[194:195], v[194:195] op_sel_hi:[1,0,0]
	v_pk_mul_f32 v[74:75], v[74:75], v[86:87]
	v_rcp_f32_e32 v78, v78
	v_rcp_f32_e32 v79, v79
	s_nop 0
	v_pk_mul_f32 v[70:71], v[66:67], v[78:79]
	v_pk_mul_f32 v[66:67], v[72:73], v[84:85] op_sel_hi:[1,0]
	v_exp_f32_e32 v66, v66
	v_exp_f32_e32 v67, v67
	v_pk_mul_f32 v[68:69], v[72:73], v[68:69]
	v_pk_fma_f32 v[66:67], v[66:67], v[194:195], v[194:195] op_sel_hi:[1,0,0]
	s_nop 0
	v_rcp_f32_e32 v66, v66
	v_rcp_f32_e32 v67, v67
	s_nop 0
	v_pk_mul_f32 v[72:73], v[68:69], v[66:67]
	v_cvt_pk_bf16_f32 v66, v74, v75
	v_cvt_pk_bf16_f32 v67, v76, v77
	v_cvt_pk_bf16_f32 v68, v70, v71
	v_add_u32_e32 v70, 0x42000, v114
	v_cvt_pk_bf16_f32 v69, v72, v73
	buffer_store_dwordx4 v[66:69], v70, s[52:55], 0 offen sc1
	s_nop 1
	v_mul_f32_e32 v68, 0xbfb8aa3b, v176
	v_mul_f32_e32 v192, v176, v176
	v_rcp_f32_e32 v192, v192
	s_nop 0
	v_pk_mul_f32 v[70:71], v[62:63], v[68:69] op_sel_hi:[1,0]
	v_pk_mul_f32 v[58:59], v[62:63], v[58:59]
	v_pk_mul_f32 v[62:63], v[64:65], v[68:69] op_sel_hi:[1,0]
	v_exp_f32_e32 v62, v62
	v_exp_f32_e32 v63, v63
	v_pk_mul_f32 v[60:61], v[64:65], v[60:61]
	v_exp_f32_e32 v70, v70
	v_pk_fma_f32 v[62:63], v[62:63], v[192:193], v[192:193] op_sel_hi:[1,0,0]
	v_exp_f32_e32 v71, v71
	v_rcp_f32_e32 v62, v62
	v_rcp_f32_e32 v63, v63
	v_pk_fma_f32 v[70:71], v[70:71], v[192:193], v[192:193] op_sel_hi:[1,0,0]
	v_pk_mul_f32 v[60:61], v[60:61], v[62:63]
	v_pk_mul_f32 v[62:63], v[54:55], v[68:69] op_sel_hi:[1,0]
	v_exp_f32_e32 v62, v62
	v_exp_f32_e32 v63, v63
	v_pk_mul_f32 v[50:51], v[54:55], v[50:51]
	v_rcp_f32_e32 v70, v70
	v_rcp_f32_e32 v71, v71
	v_pk_fma_f32 v[62:63], v[62:63], v[192:193], v[192:193] op_sel_hi:[1,0,0]
	v_pk_mul_f32 v[58:59], v[58:59], v[70:71]
	v_rcp_f32_e32 v62, v62
	v_rcp_f32_e32 v63, v63
	s_nop 0
	v_pk_mul_f32 v[54:55], v[50:51], v[62:63]
	v_pk_mul_f32 v[50:51], v[56:57], v[68:69] op_sel_hi:[1,0]
	v_exp_f32_e32 v50, v50
	v_exp_f32_e32 v51, v51
	v_pk_mul_f32 v[52:53], v[56:57], v[52:53]
	v_pk_fma_f32 v[50:51], v[50:51], v[192:193], v[192:193] op_sel_hi:[1,0,0]
	s_nop 0
	v_rcp_f32_e32 v50, v50
	v_rcp_f32_e32 v51, v51
	s_nop 0
	v_pk_mul_f32 v[56:57], v[52:53], v[50:51]
	v_cvt_pk_bf16_f32 v50, v58, v59
	v_cvt_pk_bf16_f32 v51, v60, v61
	v_cvt_pk_bf16_f32 v52, v54, v55
	v_add_u32_e32 v54, 0xb0000, v114
	v_cvt_pk_bf16_f32 v53, v56, v57
	buffer_store_dwordx4 v[50:53], v54, s[52:55], 0 offen sc1
	s_nop 1
	v_mul_f32_e32 v52, 0xbfb8aa3b, v178
	v_mul_f32_e32 v194, v178, v178
	v_rcp_f32_e32 v194, v194
	s_nop 0
	v_pk_mul_f32 v[54:55], v[46:47], v[52:53] op_sel_hi:[1,0]
	v_pk_mul_f32 v[42:43], v[46:47], v[42:43]
	v_pk_mul_f32 v[46:47], v[48:49], v[52:53] op_sel_hi:[1,0]
	v_exp_f32_e32 v46, v46
	v_exp_f32_e32 v47, v47
	v_pk_mul_f32 v[44:45], v[48:49], v[44:45]
	v_exp_f32_e32 v54, v54
	v_pk_fma_f32 v[46:47], v[46:47], v[194:195], v[194:195] op_sel_hi:[1,0,0]
	v_exp_f32_e32 v55, v55
	v_rcp_f32_e32 v46, v46
	v_rcp_f32_e32 v47, v47
	v_pk_fma_f32 v[54:55], v[54:55], v[194:195], v[194:195] op_sel_hi:[1,0,0]
	v_pk_mul_f32 v[44:45], v[44:45], v[46:47]
	v_pk_mul_f32 v[46:47], v[38:39], v[52:53] op_sel_hi:[1,0]
	v_exp_f32_e32 v46, v46
	v_exp_f32_e32 v47, v47
	v_pk_mul_f32 v[34:35], v[38:39], v[34:35]
	v_rcp_f32_e32 v54, v54
	v_rcp_f32_e32 v55, v55
	v_pk_fma_f32 v[46:47], v[46:47], v[194:195], v[194:195] op_sel_hi:[1,0,0]
	v_pk_mul_f32 v[42:43], v[42:43], v[54:55]
	v_rcp_f32_e32 v46, v46
	v_rcp_f32_e32 v47, v47
	s_nop 0
	v_pk_mul_f32 v[38:39], v[34:35], v[46:47]
	v_pk_mul_f32 v[34:35], v[40:41], v[52:53] op_sel_hi:[1,0]
	v_exp_f32_e32 v34, v34
	v_exp_f32_e32 v35, v35
	v_pk_mul_f32 v[36:37], v[40:41], v[36:37]
	v_pk_fma_f32 v[34:35], v[34:35], v[194:195], v[194:195] op_sel_hi:[1,0,0]
	s_nop 0
	v_rcp_f32_e32 v34, v34
	v_rcp_f32_e32 v35, v35
	s_nop 0
	v_pk_mul_f32 v[40:41], v[36:37], v[34:35]
	v_cvt_pk_bf16_f32 v34, v42, v43
	v_cvt_pk_bf16_f32 v35, v44, v45
	v_cvt_pk_bf16_f32 v36, v38, v39
	v_add_u32_e32 v38, 0xc6000, v114
	v_cvt_pk_bf16_f32 v37, v40, v41
	buffer_store_dwordx4 v[34:37], v38, s[52:55], 0 offen sc1
	s_nop 1
	v_mul_f32_e32 v36, 0xbfb8aa3b, v180
	v_mul_f32_e32 v192, v180, v180
	v_rcp_f32_e32 v192, v192
	s_nop 0
	v_pk_mul_f32 v[38:39], v[30:31], v[36:37] op_sel_hi:[1,0]
	v_pk_mul_f32 v[26:27], v[30:31], v[26:27]
	v_pk_mul_f32 v[30:31], v[32:33], v[36:37] op_sel_hi:[1,0]
	v_exp_f32_e32 v30, v30
	v_exp_f32_e32 v31, v31
	v_pk_mul_f32 v[28:29], v[32:33], v[28:29]
	v_exp_f32_e32 v38, v38
	v_pk_fma_f32 v[30:31], v[30:31], v[192:193], v[192:193] op_sel_hi:[1,0,0]
	v_exp_f32_e32 v39, v39
	v_rcp_f32_e32 v30, v30
	v_rcp_f32_e32 v31, v31
	v_pk_fma_f32 v[38:39], v[38:39], v[192:193], v[192:193] op_sel_hi:[1,0,0]
	v_pk_mul_f32 v[28:29], v[28:29], v[30:31]
	v_pk_mul_f32 v[30:31], v[22:23], v[36:37] op_sel_hi:[1,0]
	v_exp_f32_e32 v30, v30
	v_exp_f32_e32 v31, v31
	v_pk_mul_f32 v[18:19], v[22:23], v[18:19]
	v_rcp_f32_e32 v38, v38
	v_rcp_f32_e32 v39, v39
	v_pk_fma_f32 v[30:31], v[30:31], v[192:193], v[192:193] op_sel_hi:[1,0,0]
	v_pk_mul_f32 v[26:27], v[26:27], v[38:39]
	v_rcp_f32_e32 v30, v30
	v_rcp_f32_e32 v31, v31
	s_nop 0
	v_pk_mul_f32 v[22:23], v[18:19], v[30:31]
	v_pk_mul_f32 v[18:19], v[24:25], v[36:37] op_sel_hi:[1,0]
	v_exp_f32_e32 v18, v18
	v_exp_f32_e32 v19, v19
	v_pk_mul_f32 v[20:21], v[24:25], v[20:21]
	v_pk_fma_f32 v[18:19], v[18:19], v[192:193], v[192:193] op_sel_hi:[1,0,0]
	s_nop 0
	v_rcp_f32_e32 v18, v18
	v_rcp_f32_e32 v19, v19
	s_nop 0
	v_pk_mul_f32 v[24:25], v[20:21], v[18:19]
	v_cvt_pk_bf16_f32 v18, v26, v27
	v_cvt_pk_bf16_f32 v19, v28, v29
	v_cvt_pk_bf16_f32 v20, v22, v23
	v_add_u32_e32 v22, 0xdc000, v114
	v_cvt_pk_bf16_f32 v21, v24, v25
	buffer_store_dwordx4 v[18:21], v22, s[52:55], 0 offen sc1
	s_nop 1
	v_mul_f32_e32 v20, 0xbfb8aa3b, v190
	v_mul_f32_e32 v194, v190, v190
	v_rcp_f32_e32 v194, v194
	s_nop 0
	v_pk_mul_f32 v[22:23], v[14:15], v[20:21] op_sel_hi:[1,0]
	v_pk_mul_f32 v[10:11], v[14:15], v[10:11]
	v_pk_mul_f32 v[14:15], v[16:17], v[20:21] op_sel_hi:[1,0]
	v_exp_f32_e32 v14, v14
	v_exp_f32_e32 v15, v15
	v_pk_mul_f32 v[12:13], v[16:17], v[12:13]
	v_exp_f32_e32 v22, v22
	v_pk_fma_f32 v[14:15], v[14:15], v[194:195], v[194:195] op_sel_hi:[1,0,0]
	v_exp_f32_e32 v23, v23
	v_rcp_f32_e32 v14, v14
	v_rcp_f32_e32 v15, v15
	v_pk_fma_f32 v[22:23], v[22:23], v[194:195], v[194:195] op_sel_hi:[1,0,0]
	v_pk_mul_f32 v[12:13], v[12:13], v[14:15]
	v_pk_mul_f32 v[14:15], v[6:7], v[20:21] op_sel_hi:[1,0]
	v_exp_f32_e32 v14, v14
	v_exp_f32_e32 v15, v15
	v_pk_mul_f32 v[2:3], v[6:7], v[2:3]
	v_rcp_f32_e32 v22, v22
	v_rcp_f32_e32 v23, v23
	v_pk_fma_f32 v[14:15], v[14:15], v[194:195], v[194:195] op_sel_hi:[1,0,0]
	v_pk_mul_f32 v[10:11], v[10:11], v[22:23]
	v_rcp_f32_e32 v14, v14
	v_rcp_f32_e32 v15, v15
	s_nop 0
	v_pk_mul_f32 v[6:7], v[2:3], v[14:15]
	v_pk_mul_f32 v[2:3], v[8:9], v[20:21] op_sel_hi:[1,0]
	v_exp_f32_e32 v2, v2
	v_exp_f32_e32 v3, v3
	v_pk_mul_f32 v[4:5], v[8:9], v[4:5]
	v_pk_fma_f32 v[2:3], v[2:3], v[194:195], v[194:195] op_sel_hi:[1,0,0]
	s_nop 0
	v_rcp_f32_e32 v2, v2
	v_rcp_f32_e32 v3, v3
	s_nop 0
	v_pk_mul_f32 v[8:9], v[4:5], v[2:3]
	v_cvt_pk_bf16_f32 v2, v10, v11
	v_cvt_pk_bf16_f32 v3, v12, v13
	v_cvt_pk_bf16_f32 v4, v6, v7
	v_add_u32_e32 v6, 0xf2000, v114
	v_cvt_pk_bf16_f32 v5, v8, v9
	buffer_store_dwordx4 v[2:5], v6, s[52:55], 0 offen sc1
	s_and_saveexec_b64 s[26:27], s[10:11]
	s_cbranch_execz .LBB11_2574
	s_waitcnt vmcnt(8)
	v_fmamk_f32 v146, v146, 0x3a800000, v206
	v_mul_f32_e32 v2, 0x4b800000, v146
	v_cmp_gt_f32_e32 vcc, s77, v146
	s_nop 1
	v_cndmask_b32_e32 v2, v146, v2, vcc
	v_rsq_f32_e32 v2, v2
	s_nop 0
	v_mul_f32_e32 v3, 0x45800000, v2
	v_cndmask_b32_e32 v2, v2, v3, vcc
	v_lshl_add_u32 v3, s42, 10, v144
	ds_write_b32 v3, v2
